# sample-row tile GEMMs: all four K batches loaded up front into registers
# speedup vs baseline: 1.0301x; 1.0009x over previous
; #define MFMA16(a, b, c) __builtin_amdgcn_mfma_f32_16x16x32_bf16(a, b, c, 0, 0, 0)
; __device__ __forceinline__ void small_gemm(const bf16_t* Ab, int lda, const bf16_t* Bt, int ldb, int K, int row0, int col0, int lane, int wave, f32x4 (&acc)[2]) {
;     const int fr = lane & 15, q4 = lane >> 4, mt = wave >> 1, nt0 = (wave & 1) * 2;
;     const bf16_t* ap = Ab + (size_t)(row0 + mt * 16 + fr) * lda + q4 * 8;
;     const bf16_t* bp0 = Bt + (size_t)(col0 + nt0 * 16 + fr) * ldb + q4 * 8; const bf16_t* bp1 = bp0 + (size_t)16 * ldb;
;     acc[0] = (f32x4){0.f, 0.f, 0.f, 0.f}; acc[1] = (f32x4){0.f, 0.f, 0.f, 0.f};
;     for (int k = 0; k < K; k += 256) {
;         bf16x8 a[8], b0[8], b1[8];
; #pragma unroll
;         for (int i = 0; i < 8; ++i) { a[i] = *(const bf16x8*)(ap + k + 32 * i); b0[i] = *(const bf16x8*)(bp0 + k + 32 * i); b1[i] = *(const bf16x8*)(bp1 + k + 32 * i); }
;         __builtin_amdgcn_sched_barrier(0);
; #pragma unroll
;         for (int i = 0; i < 8; ++i) { acc[0] = MFMA16(a[i], b0[i], acc[0]); acc[1] = MFMA16(a[i], b1[i], acc[1]); }
;         __builtin_amdgcn_sched_barrier(0);
;     }
; }
.LBB0_573:
	s_and_b32 s19, s20, 0xffffffc0
	s_add_i32 s18, s19, 0x8000
	v_add_u32_e32 v0, s18, v162
	s_waitcnt lgkmcnt(0)
	v_ashrrev_i32_e32 v1, 31, v0
	s_and_b32 s25, s21, 0x3c0
	v_lshlrev_b64 v[0:1], 11, v[0:1]
	v_lshl_add_u64 v[112:113], v[10:11], 0, v[0:1]
	v_or_b32_e32 v0, s25, v27
	v_lshlrev_b32_e32 v8, 11, v0
	v_lshl_add_u64 v[114:115], v[12:13], 0, v[8:9]
	v_add_co_u32_e32 v116, vcc, s23, v114
	s_nop 1
	v_addc_co_u32_e32 v117, vcc, 0, v115, vcc
	v_mbcnt_lo_u32_b32 v32, -1, 0
	v_mbcnt_hi_u32_b32 v32, -1, v32
	v_readlane_b32 s100, v249, 3
	s_lshl_b32 s101, s100, 6
	v_add_u32_e32 v33, s101, v32
	v_lshrrev_b32_e32 v34, 5, v33
	v_and_b32_e32 v33, 31, v33
	v_lshlrev_b32_e32 v33, 4, v33
	v_lshl_add_u32 v20, v34, 11, v33
	v_add_u32_e32 v21, 0x8000, v20
	v_add_u32_e32 v22, 0x10000, v20
	v_add_u32_e32 v23, 0x18000, v20
	v_mul_u32_u24_e32 v24, 0x210, v34
	v_add_u32_e32 v24, v24, v33
	v_add_u32_e32 v25, 0x10800, v24
	v_and_b32_e32 v33, 15, v32
	v_lshrrev_b32_e32 v34, 4, v32
	v_lshlrev_b32_e32 v34, 4, v34
	s_lshr_b32 s101, s100, 1
	s_lshl_b32 s101, s101, 4
	v_add_u32_e32 v28, s101, v33
	v_mul_u32_u24_e32 v28, 0x210, v28
	v_add_u32_e32 v28, v28, v34
	v_add_u32_e32 v29, 0x10800, v28
	s_and_b32 s101, s100, 1
	s_lshl_b32 s101, s101, 5
	v_add_u32_e32 v30, s101, v33
	v_mul_u32_u24_e32 v30, 0x210, v30
	v_add_u32_e32 v30, v30, v34
	v_add_u32_e32 v30, 0x8400, v30
	v_add_u32_e32 v31, 0x10800, v30
	v_readlane_b32 s100, v249, 1
	v_readlane_b32 s101, v249, 2
	s_lshl_b32 s98, s25, 11
	s_add_u32 s98, s100, s98
	s_addc_u32 s99, s101, 0
	s_lshl_b32 s101, s18, 11
	s_add_u32 s100, s68, s101
	s_addc_u32 s101, s69, 0
	s_nop 0
	global_load_dwordx4 v[32:35], v20, s[100:101]
	global_load_dwordx4 v[36:39], v21, s[100:101]
	global_load_dwordx4 v[40:43], v22, s[100:101]
	global_load_dwordx4 v[44:47], v23, s[100:101]
	global_load_dwordx4 v[48:51], v20, s[98:99]
	global_load_dwordx4 v[52:55], v21, s[98:99]
	global_load_dwordx4 v[56:59], v22, s[98:99]
	global_load_dwordx4 v[60:63], v23, s[98:99]
	global_load_dwordx4 v[166:169], v20, s[100:101] offset:512
	global_load_dwordx4 v[170:173], v21, s[100:101] offset:512
	global_load_dwordx4 v[174:177], v22, s[100:101] offset:512
	global_load_dwordx4 v[178:181], v23, s[100:101] offset:512
	global_load_dwordx4 v[182:185], v20, s[98:99] offset:512
	global_load_dwordx4 v[186:189], v21, s[98:99] offset:512
	global_load_dwordx4 v[190:193], v22, s[98:99] offset:512
	global_load_dwordx4 v[194:197], v23, s[98:99] offset:512
	global_load_dwordx4 v[210:213], v20, s[100:101] offset:1024
	global_load_dwordx4 v[214:217], v21, s[100:101] offset:1024
	global_load_dwordx4 v[218:221], v22, s[100:101] offset:1024
	global_load_dwordx4 v[222:225], v23, s[100:101] offset:1024
	global_load_dwordx4 v[226:229], v20, s[98:99] offset:1024
	global_load_dwordx4 v[230:233], v21, s[98:99] offset:1024
	global_load_dwordx4 v[234:237], v22, s[98:99] offset:1024
	global_load_dwordx4 v[238:241], v23, s[98:99] offset:1024
	global_load_dwordx4 v[112:115], v20, s[100:101] offset:1536
	global_load_dwordx4 v[116:119], v21, s[100:101] offset:1536
	global_load_dwordx4 v[120:123], v22, s[100:101] offset:1536
	global_load_dwordx4 v[124:127], v23, s[100:101] offset:1536
	global_load_dwordx4 v[146:149], v20, s[98:99] offset:1536
	global_load_dwordx4 v[150:153], v21, s[98:99] offset:1536
	global_load_dwordx4 v[154:157], v22, s[98:99] offset:1536
	global_load_dwordx4 v[158:161], v23, s[98:99] offset:1536
	s_waitcnt vmcnt(24)
	ds_write_b128 v24, v[32:35]
	ds_write_b128 v24, v[36:39] offset:8448
	ds_write_b128 v24, v[40:43] offset:16896
	ds_write_b128 v24, v[44:47] offset:25344
	ds_write_b128 v24, v[48:51] offset:33792
	ds_write_b128 v24, v[52:55] offset:42240
	ds_write_b128 v24, v[56:59] offset:50688
	ds_write_b128 v24, v[60:63] offset:59136
	s_waitcnt lgkmcnt(0)
	s_barrier
	ds_read_b128 v[64:67], v28
	ds_read_b128 v[80:83], v30
	ds_read_b128 v[96:99], v30 offset:8448
	ds_read_b128 v[68:71], v28 offset:64
	ds_read_b128 v[84:87], v30 offset:64
	ds_read_b128 v[100:103], v30 offset:8512
	ds_read_b128 v[72:75], v28 offset:128
	ds_read_b128 v[88:91], v30 offset:128
	ds_read_b128 v[104:107], v30 offset:8576
	ds_read_b128 v[76:79], v28 offset:192
	ds_read_b128 v[92:95], v30 offset:192
	ds_read_b128 v[108:111], v30 offset:8640
	s_waitcnt lgkmcnt(9)
	v_mfma_f32_16x16x32_bf16 v[0:3], v[64:67], v[80:83], 0
	v_mfma_f32_16x16x32_bf16 v[4:7], v[64:67], v[96:99], 0
	s_waitcnt lgkmcnt(6)
	v_mfma_f32_16x16x32_bf16 v[0:3], v[68:71], v[84:87], v[0:3]
	v_mfma_f32_16x16x32_bf16 v[4:7], v[68:71], v[100:103], v[4:7]
	s_waitcnt lgkmcnt(3)
	v_mfma_f32_16x16x32_bf16 v[0:3], v[72:75], v[88:91], v[0:3]
	v_mfma_f32_16x16x32_bf16 v[4:7], v[72:75], v[104:107], v[4:7]
	s_waitcnt lgkmcnt(0)
	v_mfma_f32_16x16x32_bf16 v[0:3], v[76:79], v[92:95], v[0:3]
	v_mfma_f32_16x16x32_bf16 v[4:7], v[76:79], v[108:111], v[4:7]
	ds_read_b128 v[64:67], v28 offset:256
	ds_read_b128 v[80:83], v30 offset:256
	ds_read_b128 v[96:99], v30 offset:8704
	ds_read_b128 v[68:71], v28 offset:320
	ds_read_b128 v[84:87], v30 offset:320
	ds_read_b128 v[100:103], v30 offset:8768
	ds_read_b128 v[72:75], v28 offset:384
	ds_read_b128 v[88:91], v30 offset:384
	ds_read_b128 v[104:107], v30 offset:8832
	ds_read_b128 v[76:79], v28 offset:448
	ds_read_b128 v[92:95], v30 offset:448
	ds_read_b128 v[108:111], v30 offset:8896
	s_waitcnt lgkmcnt(9)
	v_mfma_f32_16x16x32_bf16 v[0:3], v[64:67], v[80:83], v[0:3]
	v_mfma_f32_16x16x32_bf16 v[4:7], v[64:67], v[96:99], v[4:7]
	s_waitcnt lgkmcnt(6)
	v_mfma_f32_16x16x32_bf16 v[0:3], v[68:71], v[84:87], v[0:3]
	v_mfma_f32_16x16x32_bf16 v[4:7], v[68:71], v[100:103], v[4:7]
	s_waitcnt lgkmcnt(3)
	v_mfma_f32_16x16x32_bf16 v[0:3], v[72:75], v[88:91], v[0:3]
	v_mfma_f32_16x16x32_bf16 v[4:7], v[72:75], v[104:107], v[4:7]
	s_waitcnt lgkmcnt(0)
	v_mfma_f32_16x16x32_bf16 v[0:3], v[76:79], v[92:95], v[0:3]
	v_mfma_f32_16x16x32_bf16 v[4:7], v[76:79], v[108:111], v[4:7]
	s_waitcnt vmcnt(16)
	ds_write_b128 v25, v[166:169]
	ds_write_b128 v25, v[170:173] offset:8448
	ds_write_b128 v25, v[174:177] offset:16896
	ds_write_b128 v25, v[178:181] offset:25344
	ds_write_b128 v25, v[182:185] offset:33792
	ds_write_b128 v25, v[186:189] offset:42240
	ds_write_b128 v25, v[190:193] offset:50688
	ds_write_b128 v25, v[194:197] offset:59136
	s_waitcnt lgkmcnt(0)
	s_barrier
; #define MFMA16(a, b, c) __builtin_amdgcn_mfma_f32_16x16x32_bf16(a, b, c, 0, 0, 0)
; __device__ __forceinline__ void small_gemm(const bf16_t* Ab, int lda, const bf16_t* Bt, int ldb, int K, int row0, int col0, int lane, int wave, f32x4 (&acc)[2]) {
;     const int fr = lane & 15, q4 = lane >> 4, mt = wave >> 1, nt0 = (wave & 1) * 2;
;     const bf16_t* ap = Ab + (size_t)(row0 + mt * 16 + fr) * lda + q4 * 8;
;     const bf16_t* bp0 = Bt + (size_t)(col0 + nt0 * 16 + fr) * ldb + q4 * 8; const bf16_t* bp1 = bp0 + (size_t)16 * ldb;
;     acc[0] = (f32x4){0.f, 0.f, 0.f, 0.f}; acc[1] = (f32x4){0.f, 0.f, 0.f, 0.f};
;     for (int k = 0; k < K; k += 256) {
;         bf16x8 a[8], b0[8], b1[8];
; #pragma unroll
;         for (int i = 0; i < 8; ++i) { a[i] = *(const bf16x8*)(ap + k + 32 * i); b0[i] = *(const bf16x8*)(bp0 + k + 32 * i); b1[i] = *(const bf16x8*)(bp1 + k + 32 * i); }
;         __builtin_amdgcn_sched_barrier(0);
; #pragma unroll
;         for (int i = 0; i < 8; ++i) { acc[0] = MFMA16(a[i], b0[i], acc[0]); acc[1] = MFMA16(a[i], b1[i], acc[1]); }
;         __builtin_amdgcn_sched_barrier(0);
;     }
; }
	ds_read_b128 v[64:67], v29
	ds_read_b128 v[80:83], v31
	ds_read_b128 v[96:99], v31 offset:8448
	ds_read_b128 v[68:71], v29 offset:64
	ds_read_b128 v[84:87], v31 offset:64
	ds_read_b128 v[100:103], v31 offset:8512
	ds_read_b128 v[72:75], v29 offset:128
	ds_read_b128 v[88:91], v31 offset:128
	ds_read_b128 v[104:107], v31 offset:8576
	ds_read_b128 v[76:79], v29 offset:192
	ds_read_b128 v[92:95], v31 offset:192
	ds_read_b128 v[108:111], v31 offset:8640
	s_waitcnt lgkmcnt(9)
	v_mfma_f32_16x16x32_bf16 v[0:3], v[64:67], v[80:83], v[0:3]
	v_mfma_f32_16x16x32_bf16 v[4:7], v[64:67], v[96:99], v[4:7]
	s_waitcnt lgkmcnt(6)
	v_mfma_f32_16x16x32_bf16 v[0:3], v[68:71], v[84:87], v[0:3]
	v_mfma_f32_16x16x32_bf16 v[4:7], v[68:71], v[100:103], v[4:7]
	s_waitcnt lgkmcnt(3)
	v_mfma_f32_16x16x32_bf16 v[0:3], v[72:75], v[88:91], v[0:3]
	v_mfma_f32_16x16x32_bf16 v[4:7], v[72:75], v[104:107], v[4:7]
	s_waitcnt lgkmcnt(0)
	v_mfma_f32_16x16x32_bf16 v[0:3], v[76:79], v[92:95], v[0:3]
	v_mfma_f32_16x16x32_bf16 v[4:7], v[76:79], v[108:111], v[4:7]
	ds_read_b128 v[64:67], v29 offset:256
	ds_read_b128 v[80:83], v31 offset:256
	ds_read_b128 v[96:99], v31 offset:8704
	ds_read_b128 v[68:71], v29 offset:320
	ds_read_b128 v[84:87], v31 offset:320
	ds_read_b128 v[100:103], v31 offset:8768
	ds_read_b128 v[72:75], v29 offset:384
	ds_read_b128 v[88:91], v31 offset:384
	ds_read_b128 v[104:107], v31 offset:8832
	ds_read_b128 v[76:79], v29 offset:448
	ds_read_b128 v[92:95], v31 offset:448
	ds_read_b128 v[108:111], v31 offset:8896
	s_waitcnt lgkmcnt(9)
	v_mfma_f32_16x16x32_bf16 v[0:3], v[64:67], v[80:83], v[0:3]
	v_mfma_f32_16x16x32_bf16 v[4:7], v[64:67], v[96:99], v[4:7]
	s_waitcnt lgkmcnt(6)
	v_mfma_f32_16x16x32_bf16 v[0:3], v[68:71], v[84:87], v[0:3]
	v_mfma_f32_16x16x32_bf16 v[4:7], v[68:71], v[100:103], v[4:7]
	s_waitcnt lgkmcnt(3)
	v_mfma_f32_16x16x32_bf16 v[0:3], v[72:75], v[88:91], v[0:3]
	v_mfma_f32_16x16x32_bf16 v[4:7], v[72:75], v[104:107], v[4:7]
	s_waitcnt lgkmcnt(0)
	v_mfma_f32_16x16x32_bf16 v[0:3], v[76:79], v[92:95], v[0:3]
	v_mfma_f32_16x16x32_bf16 v[4:7], v[76:79], v[108:111], v[4:7]
	s_waitcnt vmcnt(8)
	ds_write_b128 v24, v[210:213]
	ds_write_b128 v24, v[214:217] offset:8448
	ds_write_b128 v24, v[218:221] offset:16896
	ds_write_b128 v24, v[222:225] offset:25344
	ds_write_b128 v24, v[226:229] offset:33792
	ds_write_b128 v24, v[230:233] offset:42240
	ds_write_b128 v24, v[234:237] offset:50688
	ds_write_b128 v24, v[238:241] offset:59136
	s_waitcnt lgkmcnt(0)
	s_barrier
	ds_read_b128 v[64:67], v28
	ds_read_b128 v[80:83], v30
	ds_read_b128 v[96:99], v30 offset:8448
	ds_read_b128 v[68:71], v28 offset:64
	ds_read_b128 v[84:87], v30 offset:64
	ds_read_b128 v[100:103], v30 offset:8512
	ds_read_b128 v[72:75], v28 offset:128
	ds_read_b128 v[88:91], v30 offset:128
	ds_read_b128 v[104:107], v30 offset:8576
	ds_read_b128 v[76:79], v28 offset:192
	ds_read_b128 v[92:95], v30 offset:192
	ds_read_b128 v[108:111], v30 offset:8640
	s_waitcnt lgkmcnt(9)
	v_mfma_f32_16x16x32_bf16 v[0:3], v[64:67], v[80:83], v[0:3]
	v_mfma_f32_16x16x32_bf16 v[4:7], v[64:67], v[96:99], v[4:7]
	s_waitcnt lgkmcnt(6)
	v_mfma_f32_16x16x32_bf16 v[0:3], v[68:71], v[84:87], v[0:3]
	v_mfma_f32_16x16x32_bf16 v[4:7], v[68:71], v[100:103], v[4:7]
	s_waitcnt lgkmcnt(3)
	v_mfma_f32_16x16x32_bf16 v[0:3], v[72:75], v[88:91], v[0:3]
	v_mfma_f32_16x16x32_bf16 v[4:7], v[72:75], v[104:107], v[4:7]
	s_waitcnt lgkmcnt(0)
	v_mfma_f32_16x16x32_bf16 v[0:3], v[76:79], v[92:95], v[0:3]
	v_mfma_f32_16x16x32_bf16 v[4:7], v[76:79], v[108:111], v[4:7]
	ds_read_b128 v[64:67], v28 offset:256
	ds_read_b128 v[80:83], v30 offset:256
	ds_read_b128 v[96:99], v30 offset:8704
	ds_read_b128 v[68:71], v28 offset:320
	ds_read_b128 v[84:87], v30 offset:320
	ds_read_b128 v[100:103], v30 offset:8768
	ds_read_b128 v[72:75], v28 offset:384
	ds_read_b128 v[88:91], v30 offset:384
	ds_read_b128 v[104:107], v30 offset:8832
	ds_read_b128 v[76:79], v28 offset:448
	ds_read_b128 v[92:95], v30 offset:448
	ds_read_b128 v[108:111], v30 offset:8896
	s_waitcnt lgkmcnt(9)
	v_mfma_f32_16x16x32_bf16 v[0:3], v[64:67], v[80:83], v[0:3]
	v_mfma_f32_16x16x32_bf16 v[4:7], v[64:67], v[96:99], v[4:7]
	s_waitcnt lgkmcnt(6)
	v_mfma_f32_16x16x32_bf16 v[0:3], v[68:71], v[84:87], v[0:3]
	v_mfma_f32_16x16x32_bf16 v[4:7], v[68:71], v[100:103], v[4:7]
	s_waitcnt lgkmcnt(3)
	v_mfma_f32_16x16x32_bf16 v[0:3], v[72:75], v[88:91], v[0:3]
	v_mfma_f32_16x16x32_bf16 v[4:7], v[72:75], v[104:107], v[4:7]
	s_waitcnt lgkmcnt(0)
	v_mfma_f32_16x16x32_bf16 v[0:3], v[76:79], v[92:95], v[0:3]
	v_mfma_f32_16x16x32_bf16 v[4:7], v[76:79], v[108:111], v[4:7]
	s_waitcnt vmcnt(0)
	ds_write_b128 v25, v[112:115]
	ds_write_b128 v25, v[116:119] offset:8448
	ds_write_b128 v25, v[120:123] offset:16896
	ds_write_b128 v25, v[124:127] offset:25344
	ds_write_b128 v25, v[146:149] offset:33792
	ds_write_b128 v25, v[150:153] offset:42240
	ds_write_b128 v25, v[154:157] offset:50688
	ds_write_b128 v25, v[158:161] offset:59136
	s_waitcnt lgkmcnt(0)
	s_barrier
; __device__ __forceinline__ unsigned f2bf(float f) { return pk2(f, 0.f) & 0xffffu; }
; __device__ __forceinline__ float red16_sum(float x) { x = red8_sum(x); x += dppf<0x140>(x); return x; }
; #define MFMA16(a, b, c) __builtin_amdgcn_mfma_f32_16x16x32_bf16(a, b, c, 0, 0, 0)
; __device__ __forceinline__ void small_gemm(const bf16_t* Ab, int lda, const bf16_t* Bt, int ldb, int K, int row0, int col0, int lane, int wave, f32x4 (&acc)[2]) {
;     const int fr = lane & 15, q4 = lane >> 4, mt = wave >> 1, nt0 = (wave & 1) * 2;
;     const bf16_t* ap = Ab + (size_t)(row0 + mt * 16 + fr) * lda + q4 * 8;
;     const bf16_t* bp0 = Bt + (size_t)(col0 + nt0 * 16 + fr) * ldb + q4 * 8; const bf16_t* bp1 = bp0 + (size_t)16 * ldb;
;     acc[0] = (f32x4){0.f, 0.f, 0.f, 0.f}; acc[1] = (f32x4){0.f, 0.f, 0.f, 0.f};
;     for (int k = 0; k < K; k += 256) {
;         bf16x8 a[8], b0[8], b1[8];
; #pragma unroll
;         for (int i = 0; i < 8; ++i) { a[i] = *(const bf16x8*)(ap + k + 32 * i); b0[i] = *(const bf16x8*)(bp0 + k + 32 * i); b1[i] = *(const bf16x8*)(bp1 + k + 32 * i); }
;         __builtin_amdgcn_sched_barrier(0);
; #pragma unroll
;         for (int i = 0; i < 8; ++i) { acc[0] = MFMA16(a[i], b0[i], acc[0]); acc[1] = MFMA16(a[i], b1[i], acc[1]); }
;         __builtin_amdgcn_sched_barrier(0);
;     }
; }
; __global__ void __launch_bounds__(512, 2) hymba_fwd(Args A) {
;     ...
;             for (int jj = 0; jj < 4; ++jj) { const int row = row0 + (wave >> 1) * 16 + q4 * 4 + jj; float ss = 0.f;
; #pragma unroll
;                 for (int nn = 0; nn < 2; ++nn) { const int col = col0 + ((wave & 1) * 2 + nn) * 16 + fr; const float v = acc[nn][jj] + A.x_sample[(size_t)(row - MP) * DM + col];
;                     H2B[(size_t)row * DM + col] = (bf16_t)f2bf(v); ss += v * v; }
;                 ss = red16_sum(ss); if (fr == 0) atomicAdd(rowss2 + row, ss); }
	ds_read_b128 v[64:67], v29
	ds_read_b128 v[80:83], v31
	ds_read_b128 v[96:99], v31 offset:8448
	ds_read_b128 v[68:71], v29 offset:64
	ds_read_b128 v[84:87], v31 offset:64
	ds_read_b128 v[100:103], v31 offset:8512
	ds_read_b128 v[72:75], v29 offset:128
	ds_read_b128 v[88:91], v31 offset:128
	ds_read_b128 v[104:107], v31 offset:8576
	ds_read_b128 v[76:79], v29 offset:192
	ds_read_b128 v[92:95], v31 offset:192
	ds_read_b128 v[108:111], v31 offset:8640
	s_waitcnt lgkmcnt(9)
	v_mfma_f32_16x16x32_bf16 v[0:3], v[64:67], v[80:83], v[0:3]
	v_mfma_f32_16x16x32_bf16 v[4:7], v[64:67], v[96:99], v[4:7]
	s_waitcnt lgkmcnt(6)
	v_mfma_f32_16x16x32_bf16 v[0:3], v[68:71], v[84:87], v[0:3]
	v_mfma_f32_16x16x32_bf16 v[4:7], v[68:71], v[100:103], v[4:7]
	s_waitcnt lgkmcnt(3)
	v_mfma_f32_16x16x32_bf16 v[0:3], v[72:75], v[88:91], v[0:3]
	v_mfma_f32_16x16x32_bf16 v[4:7], v[72:75], v[104:107], v[4:7]
	s_waitcnt lgkmcnt(0)
	v_mfma_f32_16x16x32_bf16 v[0:3], v[76:79], v[92:95], v[0:3]
	v_mfma_f32_16x16x32_bf16 v[4:7], v[76:79], v[108:111], v[4:7]
	ds_read_b128 v[64:67], v29 offset:256
	ds_read_b128 v[80:83], v31 offset:256
	ds_read_b128 v[96:99], v31 offset:8704
	ds_read_b128 v[68:71], v29 offset:320
	ds_read_b128 v[84:87], v31 offset:320
	ds_read_b128 v[100:103], v31 offset:8768
	ds_read_b128 v[72:75], v29 offset:384
	ds_read_b128 v[88:91], v31 offset:384
	ds_read_b128 v[104:107], v31 offset:8832
	ds_read_b128 v[76:79], v29 offset:448
	ds_read_b128 v[92:95], v31 offset:448
	ds_read_b128 v[108:111], v31 offset:8896
	s_waitcnt lgkmcnt(9)
	v_mfma_f32_16x16x32_bf16 v[0:3], v[64:67], v[80:83], v[0:3]
	v_mfma_f32_16x16x32_bf16 v[4:7], v[64:67], v[96:99], v[4:7]
	s_waitcnt lgkmcnt(6)
	v_mfma_f32_16x16x32_bf16 v[0:3], v[68:71], v[84:87], v[0:3]
	v_mfma_f32_16x16x32_bf16 v[4:7], v[68:71], v[100:103], v[4:7]
	s_waitcnt lgkmcnt(3)
	v_mfma_f32_16x16x32_bf16 v[0:3], v[72:75], v[88:91], v[0:3]
	v_mfma_f32_16x16x32_bf16 v[4:7], v[72:75], v[104:107], v[4:7]
	s_waitcnt lgkmcnt(0)
	v_mfma_f32_16x16x32_bf16 v[0:3], v[76:79], v[92:95], v[0:3]
	v_mfma_f32_16x16x32_bf16 v[4:7], v[76:79], v[108:111], v[4:7]
	s_nop 4
	v_add_u32_e32 v14, s19, v26
	v_or_b32_e32 v18, s25, v132
	v_ashrrev_i32_e32 v15, 31, v14
	v_readlane_b32 s44, v249, 14
	v_lshlrev_b64 v[14:15], 12, v[14:15]
	v_readlane_b32 s46, v249, 16
	v_readlane_b32 s47, v249, 17
	v_or_b32_e32 v24, s73, v18
	v_lshlrev_b32_e32 v8, 2, v24
	v_lshl_add_u64 v[14:15], s[46:47], 0, v[14:15]
	v_add_u32_e32 v25, s73, v18
	v_lshl_add_u64 v[16:17], v[14:15], 0, v[8:9]
	v_lshlrev_b32_e32 v18, 2, v25
	v_mov_b32_e32 v19, v9
	v_lshl_add_u64 v[14:15], v[14:15], 0, v[18:19]
	global_load_dword v28, v[16:17], off
	global_load_dword v29, v[14:15], off offset:64
	v_add_u32_e32 v20, s18, v26
	v_ashrrev_i32_e32 v21, 31, v20
	v_lshlrev_b64 v[22:23], 11, v[20:21]
	v_mov_b32_e32 v15, v9
	v_lshlrev_b32_e32 v14, 1, v24
	v_lshl_add_u64 v[22:23], s[94:95], 0, v[22:23]
	v_mov_b32_e32 v17, v9
	v_lshlrev_b32_e32 v16, 1, v25
	v_lshl_add_u64 v[24:25], v[22:23], 0, v[14:15]
	v_readlane_b32 s45, v249, 15
	v_readlane_b32 s48, v249, 18
	v_readlane_b32 s49, v249, 19
	v_readlane_b32 s50, v249, 20
	v_readlane_b32 s51, v249, 21
	v_readlane_b32 s52, v249, 22
	v_readlane_b32 s53, v249, 23
	v_readlane_b32 s54, v249, 24
	v_readlane_b32 s55, v249, 25
	v_readlane_b32 s56, v249, 26
	v_readlane_b32 s57, v249, 27
	v_readlane_b32 s58, v249, 28
	v_readlane_b32 s59, v249, 29
	v_lshl_add_u64 v[22:23], v[22:23], 0, v[16:17]
	s_waitcnt vmcnt(1)
	v_add_f32_e32 v0, v0, v28
	s_waitcnt vmcnt(0)
	v_add_f32_e32 v4, v4, v29
	v_cvt_pk_bf16_f32 v29, v4, s0
	v_mul_f32_e32 v4, v4, v4
	v_fmac_f32_e32 v4, v0, v0
	v_cvt_pk_bf16_f32 v28, v0, s0
	global_store_short v[24:25], v28, off
	global_store_short v[22:23], v29, off offset:32
	v_add_f32_dpp v0, v4, v4 quad_perm:[1,0,3,2] row_mask:0xf bank_mask:0xf bound_ctrl:1
	v_mov_b32_e32 v4, v9
	s_nop 0
	v_add_f32_dpp v0, v0, v0 quad_perm:[2,3,0,1] row_mask:0xf bank_mask:0xf bound_ctrl:1
	s_nop 1
	v_add_f32_dpp v0, v0, v0 row_half_mirror row_mask:0xf bank_mask:0xf bound_ctrl:1
	s_nop 1
	v_mov_b32_dpp v4, v0 row_mirror row_mask:0xf bank_mask:0xf
	s_and_saveexec_b64 s[18:19], s[4:5]
	s_cbranch_execz .LBB0_575
	v_lshl_add_u64 v[22:23], v[20:21], 2, s[10:11]
	v_add_f32_e32 v0, v0, v4
	global_atomic_add_f32 v[22:23], v0, off

; #define MFMA16(a, b, c) __builtin_amdgcn_mfma_f32_16x16x32_bf16(a, b, c, 0, 0, 0)
; __device__ __forceinline__ void small_gemm(const bf16_t* Ab, int lda, const bf16_t* Bt, int ldb, int K, int row0, int col0, int lane, int wave, f32x4 (&acc)[2]) {
;     const int fr = lane & 15, q4 = lane >> 4, mt = wave >> 1, nt0 = (wave & 1) * 2;
;     const bf16_t* ap = Ab + (size_t)(row0 + mt * 16 + fr) * lda + q4 * 8;
;     const bf16_t* bp0 = Bt + (size_t)(col0 + nt0 * 16 + fr) * ldb + q4 * 8; const bf16_t* bp1 = bp0 + (size_t)16 * ldb;
;     acc[0] = (f32x4){0.f, 0.f, 0.f, 0.f}; acc[1] = (f32x4){0.f, 0.f, 0.f, 0.f};
;     for (int k = 0; k < K; k += 256) {
;         bf16x8 a[8], b0[8], b1[8];
; #pragma unroll
;         for (int i = 0; i < 8; ++i) { a[i] = *(const bf16x8*)(ap + k + 32 * i); b0[i] = *(const bf16x8*)(bp0 + k + 32 * i); b1[i] = *(const bf16x8*)(bp1 + k + 32 * i); }
;         __builtin_amdgcn_sched_barrier(0);
; #pragma unroll
;         for (int i = 0; i < 8; ++i) { acc[0] = MFMA16(a[i], b0[i], acc[0]); acc[1] = MFMA16(a[i], b1[i], acc[1]); }
;         __builtin_amdgcn_sched_barrier(0);
;     }
; }
.LBB0_632:
	s_and_b32 s16, s7, 0xffffffc0
	s_add_i32 s16, s16, 0x8000
	v_add_u32_e32 v0, s16, v162
	s_waitcnt lgkmcnt(0)
	v_ashrrev_i32_e32 v1, 31, v0
	s_and_b32 s15, s8, 0x3c0
	v_lshlrev_b64 v[0:1], 11, v[0:1]
	v_lshl_add_u64 v[112:113], v[8:9], 0, v[0:1]
	v_or_b32_e32 v0, s15, v17
	v_lshlrev_b32_e32 v134, 11, v0
	v_lshl_add_u64 v[114:115], v[10:11], 0, v[134:135]
	v_add_co_u32_e64 v116, s[4:5], s14, v114
	s_nop 1
	v_addc_co_u32_e64 v117, s[4:5], 0, v115, s[4:5]
	v_mbcnt_lo_u32_b32 v32, -1, 0
	v_mbcnt_hi_u32_b32 v32, -1, v32
	v_readlane_b32 s100, v249, 3
	s_lshl_b32 s101, s100, 6
	v_add_u32_e32 v33, s101, v32
	v_lshrrev_b32_e32 v34, 5, v33
	v_and_b32_e32 v33, 31, v33
	v_lshlrev_b32_e32 v33, 4, v33
	v_lshl_add_u32 v20, v34, 11, v33
	v_add_u32_e32 v21, 0x8000, v20
	v_add_u32_e32 v22, 0x10000, v20
	v_add_u32_e32 v23, 0x18000, v20
	v_mul_u32_u24_e32 v24, 0x210, v34
	v_add_u32_e32 v24, v24, v33
	v_add_u32_e32 v25, 0x10800, v24
	v_and_b32_e32 v33, 15, v32
	v_lshrrev_b32_e32 v34, 4, v32
	v_lshlrev_b32_e32 v34, 4, v34
	s_lshr_b32 s101, s100, 1
	s_lshl_b32 s101, s101, 4
	v_add_u32_e32 v28, s101, v33
	v_mul_u32_u24_e32 v28, 0x210, v28
	v_add_u32_e32 v28, v28, v34
	v_add_u32_e32 v29, 0x10800, v28
	s_and_b32 s101, s100, 1
	s_lshl_b32 s101, s101, 5
	v_add_u32_e32 v30, s101, v33
	v_mul_u32_u24_e32 v30, 0x210, v30
	v_add_u32_e32 v30, v30, v34
	v_add_u32_e32 v30, 0x8400, v30
	v_add_u32_e32 v31, 0x10800, v30
	s_lshl_b32 s98, s15, 11
	s_add_u32 s98, s70, s98
	s_addc_u32 s99, s71, 0
	s_lshl_b32 s101, s16, 11
	s_add_u32 s100, s94, s101
	s_addc_u32 s101, s95, 0
	s_nop 0
	global_load_dwordx4 v[32:35], v20, s[100:101]
	global_load_dwordx4 v[36:39], v21, s[100:101]
	global_load_dwordx4 v[40:43], v22, s[100:101]
	global_load_dwordx4 v[44:47], v23, s[100:101]
	global_load_dwordx4 v[48:51], v20, s[98:99]
	global_load_dwordx4 v[52:55], v21, s[98:99]
	global_load_dwordx4 v[56:59], v22, s[98:99]
	global_load_dwordx4 v[60:63], v23, s[98:99]
	global_load_dwordx4 v[166:169], v20, s[100:101] offset:512
	global_load_dwordx4 v[170:173], v21, s[100:101] offset:512
	global_load_dwordx4 v[174:177], v22, s[100:101] offset:512
	global_load_dwordx4 v[178:181], v23, s[100:101] offset:512
	global_load_dwordx4 v[182:185], v20, s[98:99] offset:512
	global_load_dwordx4 v[186:189], v21, s[98:99] offset:512
	global_load_dwordx4 v[190:193], v22, s[98:99] offset:512
	global_load_dwordx4 v[194:197], v23, s[98:99] offset:512
	global_load_dwordx4 v[210:213], v20, s[100:101] offset:1024
	global_load_dwordx4 v[214:217], v21, s[100:101] offset:1024
	global_load_dwordx4 v[218:221], v22, s[100:101] offset:1024
	global_load_dwordx4 v[222:225], v23, s[100:101] offset:1024
	global_load_dwordx4 v[226:229], v20, s[98:99] offset:1024
	global_load_dwordx4 v[230:233], v21, s[98:99] offset:1024
	global_load_dwordx4 v[234:237], v22, s[98:99] offset:1024
	global_load_dwordx4 v[238:241], v23, s[98:99] offset:1024
	global_load_dwordx4 v[112:115], v20, s[100:101] offset:1536
	global_load_dwordx4 v[116:119], v21, s[100:101] offset:1536
	global_load_dwordx4 v[120:123], v22, s[100:101] offset:1536
	global_load_dwordx4 v[124:127], v23, s[100:101] offset:1536
	global_load_dwordx4 v[146:149], v20, s[98:99] offset:1536
	global_load_dwordx4 v[150:153], v21, s[98:99] offset:1536
	global_load_dwordx4 v[154:157], v22, s[98:99] offset:1536
	global_load_dwordx4 v[158:161], v23, s[98:99] offset:1536
	s_waitcnt vmcnt(24)
	ds_write_b128 v24, v[32:35]
	ds_write_b128 v24, v[36:39] offset:8448
	ds_write_b128 v24, v[40:43] offset:16896
	ds_write_b128 v24, v[44:47] offset:25344
	ds_write_b128 v24, v[48:51] offset:33792
	ds_write_b128 v24, v[52:55] offset:42240
	ds_write_b128 v24, v[56:59] offset:50688
	ds_write_b128 v24, v[60:63] offset:59136
	s_waitcnt lgkmcnt(0)
	s_barrier
	ds_read_b128 v[64:67], v28
	ds_read_b128 v[80:83], v30
	ds_read_b128 v[96:99], v30 offset:8448
	ds_read_b128 v[68:71], v28 offset:64
	ds_read_b128 v[84:87], v30 offset:64
	ds_read_b128 v[100:103], v30 offset:8512
	ds_read_b128 v[72:75], v28 offset:128
	ds_read_b128 v[88:91], v30 offset:128
	ds_read_b128 v[104:107], v30 offset:8576
	ds_read_b128 v[76:79], v28 offset:192
	ds_read_b128 v[92:95], v30 offset:192
	ds_read_b128 v[108:111], v30 offset:8640
	s_waitcnt lgkmcnt(9)
	v_mfma_f32_16x16x32_bf16 v[4:7], v[64:67], v[80:83], 0
	v_mfma_f32_16x16x32_bf16 v[0:3], v[64:67], v[96:99], 0
	s_waitcnt lgkmcnt(6)
	v_mfma_f32_16x16x32_bf16 v[4:7], v[68:71], v[84:87], v[4:7]
	v_mfma_f32_16x16x32_bf16 v[0:3], v[68:71], v[100:103], v[0:3]
	s_waitcnt lgkmcnt(3)
	v_mfma_f32_16x16x32_bf16 v[4:7], v[72:75], v[88:91], v[4:7]
	v_mfma_f32_16x16x32_bf16 v[0:3], v[72:75], v[104:107], v[0:3]
	s_waitcnt lgkmcnt(0)
	v_mfma_f32_16x16x32_bf16 v[4:7], v[76:79], v[92:95], v[4:7]
	v_mfma_f32_16x16x32_bf16 v[0:3], v[76:79], v[108:111], v[0:3]
	ds_read_b128 v[64:67], v28 offset:256
	ds_read_b128 v[80:83], v30 offset:256
	ds_read_b128 v[96:99], v30 offset:8704
	ds_read_b128 v[68:71], v28 offset:320
	ds_read_b128 v[84:87], v30 offset:320
	ds_read_b128 v[100:103], v30 offset:8768
	ds_read_b128 v[72:75], v28 offset:384
	ds_read_b128 v[88:91], v30 offset:384
	ds_read_b128 v[104:107], v30 offset:8832
	ds_read_b128 v[76:79], v28 offset:448
	ds_read_b128 v[92:95], v30 offset:448
	ds_read_b128 v[108:111], v30 offset:8896
	s_waitcnt lgkmcnt(9)
	v_mfma_f32_16x16x32_bf16 v[4:7], v[64:67], v[80:83], v[4:7]
	v_mfma_f32_16x16x32_bf16 v[0:3], v[64:67], v[96:99], v[0:3]
	s_waitcnt lgkmcnt(6)
	v_mfma_f32_16x16x32_bf16 v[4:7], v[68:71], v[84:87], v[4:7]
	v_mfma_f32_16x16x32_bf16 v[0:3], v[68:71], v[100:103], v[0:3]
	s_waitcnt lgkmcnt(3)
	v_mfma_f32_16x16x32_bf16 v[4:7], v[72:75], v[88:91], v[4:7]
	v_mfma_f32_16x16x32_bf16 v[0:3], v[72:75], v[104:107], v[0:3]
	s_waitcnt lgkmcnt(0)
	v_mfma_f32_16x16x32_bf16 v[4:7], v[76:79], v[92:95], v[4:7]
	v_mfma_f32_16x16x32_bf16 v[0:3], v[76:79], v[108:111], v[0:3]
	s_waitcnt vmcnt(16)
	ds_write_b128 v25, v[166:169]
	ds_write_b128 v25, v[170:173] offset:8448
	ds_write_b128 v25, v[174:177] offset:16896
	ds_write_b128 v25, v[178:181] offset:25344
	ds_write_b128 v25, v[182:185] offset:33792
	ds_write_b128 v25, v[186:189] offset:42240
	ds_write_b128 v25, v[190:193] offset:50688
	ds_write_b128 v25, v[194:197] offset:59136
	s_waitcnt lgkmcnt(0)
	s_barrier
; #define MFMA16(a, b, c) __builtin_amdgcn_mfma_f32_16x16x32_bf16(a, b, c, 0, 0, 0)
; __device__ __forceinline__ void small_gemm(const bf16_t* Ab, int lda, const bf16_t* Bt, int ldb, int K, int row0, int col0, int lane, int wave, f32x4 (&acc)[2]) {
;     const int fr = lane & 15, q4 = lane >> 4, mt = wave >> 1, nt0 = (wave & 1) * 2;
;     const bf16_t* ap = Ab + (size_t)(row0 + mt * 16 + fr) * lda + q4 * 8;
;     const bf16_t* bp0 = Bt + (size_t)(col0 + nt0 * 16 + fr) * ldb + q4 * 8; const bf16_t* bp1 = bp0 + (size_t)16 * ldb;
;     acc[0] = (f32x4){0.f, 0.f, 0.f, 0.f}; acc[1] = (f32x4){0.f, 0.f, 0.f, 0.f};
;     for (int k = 0; k < K; k += 256) {
;         bf16x8 a[8], b0[8], b1[8];
; #pragma unroll
;         for (int i = 0; i < 8; ++i) { a[i] = *(const bf16x8*)(ap + k + 32 * i); b0[i] = *(const bf16x8*)(bp0 + k + 32 * i); b1[i] = *(const bf16x8*)(bp1 + k + 32 * i); }
;         __builtin_amdgcn_sched_barrier(0);
; #pragma unroll
;         for (int i = 0; i < 8; ++i) { acc[0] = MFMA16(a[i], b0[i], acc[0]); acc[1] = MFMA16(a[i], b1[i], acc[1]); }
;         __builtin_amdgcn_sched_barrier(0);
;     }
; }
	ds_read_b128 v[64:67], v29
	ds_read_b128 v[80:83], v31
	ds_read_b128 v[96:99], v31 offset:8448
	ds_read_b128 v[68:71], v29 offset:64
	ds_read_b128 v[84:87], v31 offset:64
	ds_read_b128 v[100:103], v31 offset:8512
	ds_read_b128 v[72:75], v29 offset:128
	ds_read_b128 v[88:91], v31 offset:128
	ds_read_b128 v[104:107], v31 offset:8576
	ds_read_b128 v[76:79], v29 offset:192
	ds_read_b128 v[92:95], v31 offset:192
	ds_read_b128 v[108:111], v31 offset:8640
	s_waitcnt lgkmcnt(9)
	v_mfma_f32_16x16x32_bf16 v[4:7], v[64:67], v[80:83], v[4:7]
	v_mfma_f32_16x16x32_bf16 v[0:3], v[64:67], v[96:99], v[0:3]
	s_waitcnt lgkmcnt(6)
	v_mfma_f32_16x16x32_bf16 v[4:7], v[68:71], v[84:87], v[4:7]
	v_mfma_f32_16x16x32_bf16 v[0:3], v[68:71], v[100:103], v[0:3]
	s_waitcnt lgkmcnt(3)
	v_mfma_f32_16x16x32_bf16 v[4:7], v[72:75], v[88:91], v[4:7]
	v_mfma_f32_16x16x32_bf16 v[0:3], v[72:75], v[104:107], v[0:3]
	s_waitcnt lgkmcnt(0)
	v_mfma_f32_16x16x32_bf16 v[4:7], v[76:79], v[92:95], v[4:7]
	v_mfma_f32_16x16x32_bf16 v[0:3], v[76:79], v[108:111], v[0:3]
	ds_read_b128 v[64:67], v29 offset:256
	ds_read_b128 v[80:83], v31 offset:256
	ds_read_b128 v[96:99], v31 offset:8704
	ds_read_b128 v[68:71], v29 offset:320
	ds_read_b128 v[84:87], v31 offset:320
	ds_read_b128 v[100:103], v31 offset:8768
	ds_read_b128 v[72:75], v29 offset:384
	ds_read_b128 v[88:91], v31 offset:384
	ds_read_b128 v[104:107], v31 offset:8832
	ds_read_b128 v[76:79], v29 offset:448
	ds_read_b128 v[92:95], v31 offset:448
	ds_read_b128 v[108:111], v31 offset:8896
	s_waitcnt lgkmcnt(9)
	v_mfma_f32_16x16x32_bf16 v[4:7], v[64:67], v[80:83], v[4:7]
	v_mfma_f32_16x16x32_bf16 v[0:3], v[64:67], v[96:99], v[0:3]
	s_waitcnt lgkmcnt(6)
	v_mfma_f32_16x16x32_bf16 v[4:7], v[68:71], v[84:87], v[4:7]
	v_mfma_f32_16x16x32_bf16 v[0:3], v[68:71], v[100:103], v[0:3]
	s_waitcnt lgkmcnt(3)
	v_mfma_f32_16x16x32_bf16 v[4:7], v[72:75], v[88:91], v[4:7]
	v_mfma_f32_16x16x32_bf16 v[0:3], v[72:75], v[104:107], v[0:3]
	s_waitcnt lgkmcnt(0)
	v_mfma_f32_16x16x32_bf16 v[4:7], v[76:79], v[92:95], v[4:7]
	v_mfma_f32_16x16x32_bf16 v[0:3], v[76:79], v[108:111], v[0:3]
	s_waitcnt vmcnt(8)
	ds_write_b128 v24, v[210:213]
	ds_write_b128 v24, v[214:217] offset:8448
	ds_write_b128 v24, v[218:221] offset:16896
	ds_write_b128 v24, v[222:225] offset:25344
	ds_write_b128 v24, v[226:229] offset:33792
	ds_write_b128 v24, v[230:233] offset:42240
	ds_write_b128 v24, v[234:237] offset:50688
	ds_write_b128 v24, v[238:241] offset:59136
	s_waitcnt lgkmcnt(0)
	s_barrier
	ds_read_b128 v[64:67], v28
	ds_read_b128 v[80:83], v30
	ds_read_b128 v[96:99], v30 offset:8448
	ds_read_b128 v[68:71], v28 offset:64
	ds_read_b128 v[84:87], v30 offset:64
	ds_read_b128 v[100:103], v30 offset:8512
	ds_read_b128 v[72:75], v28 offset:128
	ds_read_b128 v[88:91], v30 offset:128
	ds_read_b128 v[104:107], v30 offset:8576
	ds_read_b128 v[76:79], v28 offset:192
	ds_read_b128 v[92:95], v30 offset:192
	ds_read_b128 v[108:111], v30 offset:8640
	s_waitcnt lgkmcnt(9)
	v_mfma_f32_16x16x32_bf16 v[4:7], v[64:67], v[80:83], v[4:7]
	v_mfma_f32_16x16x32_bf16 v[0:3], v[64:67], v[96:99], v[0:3]
	s_waitcnt lgkmcnt(6)
	v_mfma_f32_16x16x32_bf16 v[4:7], v[68:71], v[84:87], v[4:7]
	v_mfma_f32_16x16x32_bf16 v[0:3], v[68:71], v[100:103], v[0:3]
	s_waitcnt lgkmcnt(3)
	v_mfma_f32_16x16x32_bf16 v[4:7], v[72:75], v[88:91], v[4:7]
	v_mfma_f32_16x16x32_bf16 v[0:3], v[72:75], v[104:107], v[0:3]
	s_waitcnt lgkmcnt(0)
	v_mfma_f32_16x16x32_bf16 v[4:7], v[76:79], v[92:95], v[4:7]
	v_mfma_f32_16x16x32_bf16 v[0:3], v[76:79], v[108:111], v[0:3]
	ds_read_b128 v[64:67], v28 offset:256
	ds_read_b128 v[80:83], v30 offset:256
	ds_read_b128 v[96:99], v30 offset:8704
	ds_read_b128 v[68:71], v28 offset:320
	ds_read_b128 v[84:87], v30 offset:320
	ds_read_b128 v[100:103], v30 offset:8768
	ds_read_b128 v[72:75], v28 offset:384
	ds_read_b128 v[88:91], v30 offset:384
	ds_read_b128 v[104:107], v30 offset:8832
	ds_read_b128 v[76:79], v28 offset:448
	ds_read_b128 v[92:95], v30 offset:448
	ds_read_b128 v[108:111], v30 offset:8896
	s_waitcnt lgkmcnt(9)
	v_mfma_f32_16x16x32_bf16 v[4:7], v[64:67], v[80:83], v[4:7]
	v_mfma_f32_16x16x32_bf16 v[0:3], v[64:67], v[96:99], v[0:3]
	s_waitcnt lgkmcnt(6)
	v_mfma_f32_16x16x32_bf16 v[4:7], v[68:71], v[84:87], v[4:7]
	v_mfma_f32_16x16x32_bf16 v[0:3], v[68:71], v[100:103], v[0:3]
	s_waitcnt lgkmcnt(3)
	v_mfma_f32_16x16x32_bf16 v[4:7], v[72:75], v[88:91], v[4:7]
	v_mfma_f32_16x16x32_bf16 v[0:3], v[72:75], v[104:107], v[0:3]
	s_waitcnt lgkmcnt(0)
	v_mfma_f32_16x16x32_bf16 v[4:7], v[76:79], v[92:95], v[4:7]
	v_mfma_f32_16x16x32_bf16 v[0:3], v[76:79], v[108:111], v[0:3]
	s_waitcnt vmcnt(0)
	ds_write_b128 v25, v[112:115]
	ds_write_b128 v25, v[116:119] offset:8448
	ds_write_b128 v25, v[120:123] offset:16896
	ds_write_b128 v25, v[124:127] offset:25344
	ds_write_b128 v25, v[146:149] offset:33792
	ds_write_b128 v25, v[150:153] offset:42240
	ds_write_b128 v25, v[154:157] offset:50688
	ds_write_b128 v25, v[158:161] offset:59136
	s_waitcnt lgkmcnt(0)
	s_barrier
; __device__ __forceinline__ unsigned f2bf(float f) { return pk2(f, 0.f) & 0xffffu; }
; __device__ __forceinline__ float red16_sum(float x) { x = red8_sum(x); x += dppf<0x140>(x); return x; }
; __device__ __forceinline__ float sigmoidf_(float x) { return __builtin_amdgcn_rcpf(1.f + __expf(-x)); }
; __global__ void __launch_bounds__(512, 2) hymba_fwd(Args A) {
;     ...
;         for (int tile = blockIdx.x; tile < 256; tile += gridDim.x) {
;             const int row0 = MP + (tile >> 4) * 64, col0 = (tile & 15) * 64; f32x4 acc[2];
;             small_gemm(H2B, DM, Wpg_t, DM, DM, row0, col0, lane, wave, acc);
; #pragma unroll
;             for (int jj = 0; jj < 4; ++jj) { const int row = row0 + (wave >> 1) * 16 + q4 * 4 + jj; float ss = 0.f;
;                 const float rstd = __builtin_amdgcn_rsqf(rowss2[row] * (1.f / DM) + NORM_EPS);
; #pragma unroll
;                 for (int nn = 0; nn < 2; ++nn) { const int col = col0 + ((wave & 1) * 2 + nn) * 16 + fr; const size_t o = (size_t)row * DM + col;
;                     const float v = bf2f(H2B[o]) + sigmoidf_(acc[nn][jj] * rstd) * bf2f(PP[o]); XN[o] = (bf16_t)f2bf(v); ss += v * v; }
;                 ss = red16_sum(ss); if (fr == 0) atomicAdd(rowss3 + row, ss); }
	ds_read_b128 v[64:67], v29
	ds_read_b128 v[80:83], v31
	ds_read_b128 v[96:99], v31 offset:8448
	ds_read_b128 v[68:71], v29 offset:64
	ds_read_b128 v[84:87], v31 offset:64
	ds_read_b128 v[100:103], v31 offset:8512
	ds_read_b128 v[72:75], v29 offset:128
	ds_read_b128 v[88:91], v31 offset:128
	ds_read_b128 v[104:107], v31 offset:8576
	ds_read_b128 v[76:79], v29 offset:192
	ds_read_b128 v[92:95], v31 offset:192
	ds_read_b128 v[108:111], v31 offset:8640
	s_waitcnt lgkmcnt(9)
	v_mfma_f32_16x16x32_bf16 v[4:7], v[64:67], v[80:83], v[4:7]
	v_mfma_f32_16x16x32_bf16 v[0:3], v[64:67], v[96:99], v[0:3]
	s_waitcnt lgkmcnt(6)
	v_mfma_f32_16x16x32_bf16 v[4:7], v[68:71], v[84:87], v[4:7]
	v_mfma_f32_16x16x32_bf16 v[0:3], v[68:71], v[100:103], v[0:3]
	s_waitcnt lgkmcnt(3)
	v_mfma_f32_16x16x32_bf16 v[4:7], v[72:75], v[88:91], v[4:7]
	v_mfma_f32_16x16x32_bf16 v[0:3], v[72:75], v[104:107], v[0:3]
	s_waitcnt lgkmcnt(0)
	v_mfma_f32_16x16x32_bf16 v[4:7], v[76:79], v[92:95], v[4:7]
	v_mfma_f32_16x16x32_bf16 v[0:3], v[76:79], v[108:111], v[0:3]
	ds_read_b128 v[64:67], v29 offset:256
	ds_read_b128 v[80:83], v31 offset:256
	ds_read_b128 v[96:99], v31 offset:8704
	ds_read_b128 v[68:71], v29 offset:320
	ds_read_b128 v[84:87], v31 offset:320
	ds_read_b128 v[100:103], v31 offset:8768
	ds_read_b128 v[72:75], v29 offset:384
	ds_read_b128 v[88:91], v31 offset:384
	ds_read_b128 v[104:107], v31 offset:8832
	ds_read_b128 v[76:79], v29 offset:448
	ds_read_b128 v[92:95], v31 offset:448
	ds_read_b128 v[108:111], v31 offset:8896
	s_waitcnt lgkmcnt(9)
	v_mfma_f32_16x16x32_bf16 v[4:7], v[64:67], v[80:83], v[4:7]
	v_mfma_f32_16x16x32_bf16 v[0:3], v[64:67], v[96:99], v[0:3]
	s_waitcnt lgkmcnt(6)
	v_mfma_f32_16x16x32_bf16 v[4:7], v[68:71], v[84:87], v[4:7]
	v_mfma_f32_16x16x32_bf16 v[0:3], v[68:71], v[100:103], v[0:3]
	s_waitcnt lgkmcnt(3)
	v_mfma_f32_16x16x32_bf16 v[4:7], v[72:75], v[88:91], v[4:7]
	v_mfma_f32_16x16x32_bf16 v[0:3], v[72:75], v[104:107], v[0:3]
	s_waitcnt lgkmcnt(0)
	v_mfma_f32_16x16x32_bf16 v[4:7], v[76:79], v[92:95], v[4:7]
	v_mfma_f32_16x16x32_bf16 v[0:3], v[76:79], v[108:111], v[0:3]
	v_add_u32_e32 v12, s16, v16
	v_ashrrev_i32_e32 v13, 31, v12
	v_lshl_add_u64 v[14:15], v[12:13], 2, s[10:11]
	global_load_dword v26, v[14:15], off
	v_or_b32_e32 v27, s15, v132
	v_or_b32_e32 v19, s73, v27
	v_lshlrev_b64 v[14:15], 10, v[12:13]
	v_or_b32_e32 v20, v14, v19
	v_mov_b32_e32 v21, v15
	v_lshlrev_b64 v[22:23], 1, v[20:21]
	v_lshl_add_u64 v[20:21], s[94:95], 0, v[22:23]
	v_lshl_add_u64 v[24:25], s[76:77], 0, v[22:23]
	global_load_ushort v28, v[20:21], off
	global_load_ushort v29, v[24:25], off
	v_lshl_add_u64 v[22:23], s[68:69], 0, v[22:23]
	s_waitcnt vmcnt(2)
	v_fmamk_f32 v20, v26, 0x3a800000, v18
	v_rsq_f32_e32 v21, v20
	v_or_b32_e32 v20, s6, v27
	v_or_b32_e32 v14, v14, v20
	v_lshlrev_b64 v[14:15], 1, v[14:15]
	v_mul_f32_e32 v4, v21, v4
	v_mul_f32_e32 v4, 0xbfb8aa3b, v4
	v_exp_f32_e32 v4, v4
	s_waitcnt vmcnt(1)
	v_lshlrev_b32_e32 v28, 16, v28
	s_waitcnt vmcnt(0)
	v_lshlrev_b32_e32 v29, 16, v29
	v_lshl_add_u64 v[24:25], s[94:95], 0, v[14:15]
	v_add_f32_e32 v4, 1.0, v4
	v_rcp_f32_e32 v4, v4
	v_lshl_add_u64 v[26:27], s[76:77], 0, v[14:15]
	v_mul_f32_e32 v0, v21, v0
	v_mul_f32_e32 v0, 0xbfb8aa3b, v0
	v_fmac_f32_e32 v28, v4, v29
	v_cvt_pk_bf16_f32 v4, v28, s0
	global_store_short v[22:23], v4, off
	global_load_ushort v4, v[24:25], off
	s_nop 0
	global_load_ushort v22, v[26:27], off
	v_exp_f32_e32 v0, v0
	v_lshl_add_u64 v[14:15], s[68:69], 0, v[14:15]
	v_add_f32_e32 v0, 1.0, v0
	v_rcp_f32_e32 v0, v0
	s_waitcnt vmcnt(1)
	v_lshlrev_b32_e32 v4, 16, v4
	s_waitcnt vmcnt(0)
	v_lshlrev_b32_e32 v21, 16, v22
	v_fmac_f32_e32 v4, v0, v21
	v_cvt_pk_bf16_f32 v0, v4, s0
	v_mul_f32_e32 v4, v4, v4
	v_fmac_f32_e32 v4, v28, v28
	global_store_short v[14:15], v0, off
	s_nop 0
	v_add_f32_dpp v0, v4, v4 quad_perm:[1,0,3,2] row_mask:0xf bank_mask:0xf bound_ctrl:1
	v_mov_b32_e32 v4, 0
	s_nop 0
	v_add_f32_dpp v0, v0, v0 quad_perm:[2,3,0,1] row_mask:0xf bank_mask:0xf bound_ctrl:1
	s_nop 1
	v_add_f32_dpp v0, v0, v0 row_half_mirror row_mask:0xf bank_mask:0xf bound_ctrl:1
	s_nop 1
	v_mov_b32_dpp v4, v0 row_mirror row_mask:0xf bank_mask:0xf
	s_and_saveexec_b64 s[4:5], vcc
	s_cbranch_execz .LBB0_634
	v_lshl_add_u64 v[14:15], v[12:13], 2, s[12:13]
	v_add_f32_e32 v0, v0, v4
	global_atomic_add_f32 v[14:15], v0, off
